# XCD-local barriers after G2/G3/G4 (guard: each blockIdx&7 group on one XCC, 8 distinct XCCs), rest = stack14
# speedup vs baseline: 1.0322x; 1.0322x over previous
; #define LAS __attribute__((address_space(3)))
; __device__ __forceinline__ unsigned xb_add(unsigned* p, unsigned v) { return __hip_atomic_fetch_add(p, v, __ATOMIC_RELAXED, __HIP_MEMORY_SCOPE_AGENT); }
; __device__ __forceinline__ unsigned xb_xcc_id() { return (unsigned)__builtin_amdgcn_s_getreg((3 << 11) | 20) & 0xFu; }
; __device__ __forceinline__ XcdBarrier xcd_barrier_post(unsigned* bar, volatile LAS unsigned* st) {
;     XcdBarrier b; b.bar = bar; b.x = xb_xcc_id(); b.st = st;
;     if (threadIdx.x == 0) (void)xb_add(&bar[XB_XCNT(b.x)], 1u);
;     return b;
; }
; __device__ __forceinline__ void xcd_barrier(const XcdBarrier& b) {
;     ...
;     if (threadIdx.x == 0) {
;         unsigned* bar = b.bar;
;         __builtin_amdgcn_s_waitcnt(0);
;         unsigned nloc = b.st[0], nx = b.st[1];
;         if (nloc == 0u) { xcd_barrier_complete(bar, b.x, nloc, nx); b.st[0] = nloc; b.st[1] = nx; }
;         const unsigned old = xb_add(&bar[XB_XSUB(b.x)], 1u);
;         const unsigned gen = old / nloc;
;         if (old + 1u == (gen + 1u) * nloc) {
;             __builtin_amdgcn_fence(__ATOMIC_RELEASE, "agent");
;             asm volatile("s_waitcnt vmcnt(0)" ::: "memory");
;             const unsigned og = xb_add(&bar[XB_TOP], 1u);
;             const unsigned tg = og / nx;
;             if (og + 1u == (tg + 1u) * nx) xb_add(&bar[XB_TOPGEN], 1u);
.LBB0_93:
	s_and_b32 s98, s67, 7
	s_lshl_b32 s98, s98, 2
	s_add_i32 s98, s98, 0x3600
	s_lshl_b32 s99, 1, s2
	v_readlane_b32 s100, v252, 8
	v_readlane_b32 s101, v252, 9
	v_mov_b32_e32 v6, s98
	v_mov_b32_e32 v7, s99
	s_nop 4
	global_atomic_or v6, v7, s[100:101]
	s_waitcnt vmcnt(0)
	s_lshl_b32 s3, s2, 8
	v_readlane_b32 s4, v252, 8
	v_readlane_b32 s5, v252, 9
	s_add_u32 s4, s4, s3
	s_addc_u32 s5, s5, 0
	v_mov_b32_e32 v2, 0x1000
	v_mov_b32_e32 v4, 1
	v_sub_u32_e32 v5, 0, v3
	global_atomic_add v4, v2, v4, s[4:5] offset:1024 sc0
	v_cvt_f32_u32_e32 v2, v3
	v_rcp_iflag_f32_e32 v2, v2
	s_nop 0
	v_mul_f32_e32 v2, 0x4f7ffffe, v2
	v_cvt_u32_f32_e32 v2, v2
	v_mul_lo_u32 v5, v5, v2
	v_mul_hi_u32 v5, v2, v5
	v_add_u32_e32 v2, v2, v5
	s_waitcnt vmcnt(0)
	v_mul_hi_u32 v2, v4, v2
	v_mul_lo_u32 v5, v2, v3
	v_sub_u32_e32 v5, v4, v5
	v_add_u32_e32 v6, 1, v2
	v_cmp_ge_u32_e32 vcc, v5, v3
	v_add_u32_e32 v4, 1, v4
	s_nop 0
	v_cndmask_b32_e32 v2, v2, v6, vcc
	v_sub_u32_e32 v6, v5, v3
	v_cndmask_b32_e32 v5, v5, v6, vcc
	v_add_u32_e32 v6, 1, v2
	v_cmp_ge_u32_e32 vcc, v5, v3
	s_nop 1
	v_cndmask_b32_e32 v2, v2, v6, vcc
	v_mul_lo_u32 v5, v3, v2
	v_add_u32_e32 v3, v5, v3
	v_cmp_ne_u32_e32 vcc, v4, v3
	s_waitcnt lgkmcnt(0)
	v_add_u32_e32 v5, 1, v2
	v_mul_lo_u32 v5, v5, v1
	v_readlane_b32 s98, v252, 8
	v_readlane_b32 s99, v252, 9
	v_mov_b32_e32 v7, 0x3400
	v_mov_b32_e32 v8, 1
	s_nop 4
	s_cbranch_vccnz .Lxb_p0_nl
	buffer_wbl2 sc1
	s_waitcnt vmcnt(0)
	global_atomic_add v7, v8, s[98:99]
	buffer_inv sc1
	s_branch .Lxb_p0_poll

; __device__ __forceinline__ void xcd_barrier(const XcdBarrier& b) {
;     ...
;         unsigned nloc = b.st[0], nx = b.st[1];
;         if (nloc == 0u) { xcd_barrier_complete(bar, b.x, nloc, nx); b.st[0] = nloc; b.st[1] = nx; }
.Lxb_p0_done:
	v_mov_b32_e32 v9, 0x3600
	global_load_dwordx4 v[10:13], v9, s[98:99] sc1
	global_load_dwordx4 v[14:17], v9, s[98:99] offset:16 sc1
	s_waitcnt vmcnt(0)
	v_or_b32_e32 v9, v10, v11
	v_or3_b32 v9, v9, v12, v13
	v_or3_b32 v9, v9, v14, v15
	v_or3_b32 v9, v9, v16, v17
	v_bcnt_u32_b32 v9, v9, 0
	v_bcnt_u32_b32 v10, v10, 0
	v_bcnt_u32_b32 v10, v11, v10
	v_bcnt_u32_b32 v10, v12, v10
	v_bcnt_u32_b32 v10, v13, v10
	v_bcnt_u32_b32 v10, v14, v10
	v_bcnt_u32_b32 v10, v15, v10
	v_bcnt_u32_b32 v10, v16, v10
	v_bcnt_u32_b32 v10, v17, v10
	v_cmp_ne_u32_e32 vcc, 8, v9
	v_cndmask_b32_e64 v9, 0, 1, vcc
	v_cmp_ne_u32_e32 vcc, 8, v10
	v_cndmask_b32_e64 v10, 0, 1, vcc
	v_cmp_ne_u32_e32 vcc, 8, v1
	v_cndmask_b32_e64 v11, 0, 1, vcc
	v_or3_b32 v9, v9, v10, v11
	v_mov_b32_e32 v10, 0x21ff8
	ds_write_b32 v10, v9
